# halfbar + first QK MFMA of the iteration issued right after the iteration barrier (ahead of LDS-DMA issue and bookkeeping)
# speedup vs baseline: 1.0105x; 1.0026x over previous
; #define SBAR() __builtin_amdgcn_sched_barrier(0)
; #define ATT_MFMA_SETTLE() asm volatile("s_nop 15\n\ts_nop 15" ::: "memory")
; #define ATT_BAR() asm volatile("s_waitcnt lgkmcnt(0)\n\ts_barrier" ::: "memory")
; #define KLOAD(sl_) k_load_nope(k0, k1, KN_lds + (sl_) * SHM_KN, r32, hi)
; #define WAIT_TILES2() do { if (wid < 4) { ATT_WAITV(6); } else { ATT_WAITV(4); } } while (0)
; __device__ __forceinline__ void sm_raise(f32x16& p0, f32x16& p1, f32x16& nm, float delta) {
;   const f32x2 d2 = {delta, delta};
; #pragma unroll
;   for (int r = 0; r < 16; r += 2) { const f32x2 t = (f32x2){p0[r], p0[r + 1]} - d2; p0[r] = t.x; p0[r + 1] = t.y; const f32x2 w = (f32x2){p1[r], p1[r + 1]} - d2; p1[r] = w.x; p1[r + 1] = w.y;
;     const f32x2 n_ = (f32x2){nm[r], nm[r + 1]} - d2; nm[r] = n_.x; nm[r + 1] = n_.y; }
; }
; __device__ __forceinline__ void attn_unit(const bf16_t* __restrict__ Qb, const unsigned char* __restrict__ Kn, const unsigned char* __restrict__ Vp, const unsigned char* __restrict__ Kp, ...
;     ...
;   KLOAD(0); qk_mma(pA0, pA1, k0, k1, KR_lds, qf, nm, r32, hi, sc); ATT_MFMA_SETTLE(); SBAR(); KLOAD(1); partialSM(pA0, pA1, nm, alA, true);
;   WAIT_TILES2(); ATT_BAR();
;   ISSUE(5, 5 * KVBLK);
;   int s0 = 1;
.LBB0_649:
	s_and_b32 s7, s7, 0x3fffffc0
	s_lshl_b32 s7, s7, 2
	s_add_i32 s7, s7, 0
	v_max_f32_e32 v0, v36, v36
	v_max_f32_e32 v1, v37, v37
	s_add_i32 s7, s7, 0x1e000
	s_add_i32 s57, s8, 0x18000
	v_max_f32_e32 v0, v0, v1
	s_add_u32 s58, s3, s82
	v_add_f32_e32 v0, 0xbfe75768, v0
	s_addc_u32 s59, s72, s83
	v_sub_f32_e32 v115, v35, v0
	v_sub_f32_e32 v114, v34, v0
	v_sub_f32_e32 v113, v33, v0
	v_sub_f32_e32 v112, v32, v0
	v_sub_f32_e32 v111, v31, v0
	v_sub_f32_e32 v110, v30, v0
	v_sub_f32_e32 v109, v29, v0
	v_sub_f32_e32 v108, v28, v0
	v_sub_f32_e32 v107, v27, v0
	v_sub_f32_e32 v106, v26, v0
	v_sub_f32_e32 v105, v25, v0
	v_sub_f32_e32 v104, v24, v0
	v_sub_f32_e32 v103, v23, v0
	v_sub_f32_e32 v102, v22, v0
	v_sub_f32_e32 v101, v21, v0
	v_sub_f32_e32 v100, v20, v0
	v_sub_f32_e32 v99, v19, v0
	v_sub_f32_e32 v98, v18, v0
	v_sub_f32_e32 v97, v17, v0
	v_sub_f32_e32 v96, v16, v0
	v_sub_f32_e32 v95, v15, v0
	v_sub_f32_e32 v94, v14, v0
	v_sub_f32_e32 v93, v13, v0
	v_sub_f32_e32 v92, v12, v0
	v_sub_f32_e32 v91, v11, v0
	v_sub_f32_e32 v90, v10, v0
	v_sub_f32_e32 v89, v9, v0
	v_sub_f32_e32 v88, v8, v0
	v_sub_f32_e32 v87, v7, v0
	v_sub_f32_e32 v86, v6, v0
	v_sub_f32_e32 v85, v5, v0
	v_sub_f32_e32 v84, v4, v0
	v_sub_f32_e32 v68, 0x3fe75768, v0
	v_add_u32_e32 v0, 0, v230
	v_lshl_add_u64 v[210:211], s[58:59], 0, v[2:3]
	s_add_u32 s58, s76, s49
	v_add_u32_e32 v239, v0, v231
	v_add_u32_e32 v240, v0, v232
	s_addc_u32 s59, s77, 0
	s_lshl_b32 s2, s2, 15
	v_lshlrev_b32_e32 v0, 12, v55
	v_or3_b32 v2, s2, v0, v56
	v_lshl_add_u64 v[0:1], s[58:59], 0, v[2:3]
	s_lshl_b32 s58, s74, 20
	s_lshl_b64 s[38:39], s[38:39], 7
	s_add_u32 s38, s58, s38
	s_addc_u32 s39, 0, s39
	v_add_u32_e32 v2, s9, v54
	v_lshl_add_u64 v[4:5], s[38:39], 0, v[2:3]
	v_mov_b32_e32 v14, v3
	v_mov_b32_e32 v15, v3
	v_lshl_add_u64 v[212:213], s[34:35], 0, v[0:1]
	v_lshl_add_u64 v[214:215], s[44:45], 0, v[4:5]
	v_lshl_add_u64 v[216:217], s[46:47], 0, v[0:1]
	v_lshl_add_u64 v[218:219], s[40:41], 0, v[4:5]
	v_mov_b32_e32 v0, v3
	v_mov_b32_e32 v1, v3
	v_mov_b32_e32 v2, v3
	v_mov_b32_e32 v4, v3
	v_mov_b32_e32 v5, v3
	v_mov_b32_e32 v6, v3
	v_mov_b32_e32 v7, v3
	v_mov_b32_e32 v8, v3
	v_mov_b32_e32 v9, v3
	v_mov_b32_e32 v10, v3
	v_mov_b32_e32 v11, v3
	v_mov_b32_e32 v12, v3
	v_mov_b32_e32 v13, v3
	v_mov_b64_e32 v[66:67], v[14:15]
	v_mov_b64_e32 v[50:51], v[14:15]
	v_mov_b64_e32 v[34:35], v[14:15]
	v_mov_b64_e32 v[64:65], v[12:13]
	v_mov_b64_e32 v[62:63], v[10:11]
	v_mov_b64_e32 v[60:61], v[8:9]
	v_mov_b64_e32 v[58:59], v[6:7]
	v_mov_b64_e32 v[56:57], v[4:5]
	v_mov_b64_e32 v[54:55], v[2:3]
	v_mov_b64_e32 v[52:53], v[0:1]
	v_mov_b64_e32 v[48:49], v[12:13]
	v_mov_b64_e32 v[46:47], v[10:11]
	v_mov_b64_e32 v[44:45], v[8:9]
	v_mov_b64_e32 v[42:43], v[6:7]
	v_mov_b64_e32 v[40:41], v[4:5]
	v_mov_b64_e32 v[38:39], v[2:3]
	v_mov_b64_e32 v[36:37], v[0:1]
	v_mov_b64_e32 v[32:33], v[12:13]
	v_mov_b64_e32 v[30:31], v[10:11]
	v_mov_b64_e32 v[28:29], v[8:9]
	v_mov_b64_e32 v[26:27], v[6:7]
	v_mov_b64_e32 v[24:25], v[4:5]
	v_mov_b64_e32 v[22:23], v[2:3]
	v_mov_b64_e32 v[20:21], v[0:1]
	v_mov_b64_e32 v[18:19], v[14:15]
	v_mov_b32_e32 v69, v68
	v_mov_b32_e32 v70, v68
	v_mov_b32_e32 v71, v68
	v_mov_b32_e32 v72, v68
	v_mov_b32_e32 v73, v68
	v_mov_b32_e32 v74, v68
	v_mov_b32_e32 v75, v68
	v_mov_b32_e32 v76, v68
	v_mov_b32_e32 v77, v68
	v_mov_b32_e32 v78, v68
	v_mov_b32_e32 v79, v68
	v_mov_b32_e32 v80, v68
	v_mov_b32_e32 v81, v68
	v_mov_b32_e32 v82, v68
	v_mov_b32_e32 v83, v68
	v_lshl_add_u32 v228, v220, 2, s7
	v_lshlrev_b32_e32 v227, 4, v221
	s_mov_b32 s2, 7
	v_mov_b32_e32 v241, 1.0
	v_mov_b32_e32 v229, 0
	s_mov_b32 s62, 1
	v_mov_b64_e32 v[16:17], v[12:13]
	v_mov_b64_e32 v[14:15], v[10:11]
	v_mov_b64_e32 v[12:13], v[8:9]
	v_mov_b64_e32 v[10:11], v[6:7]
	v_mov_b64_e32 v[8:9], v[4:5]
	v_mov_b64_e32 v[6:7], v[2:3]
	v_mov_b64_e32 v[4:5], v[0:1]
	s_movk_i32 s74, 0x3000
	.p2align 6
	s_waitcnt lgkmcnt(0)
	v_mfma_f32_32x32x64_f8f6f4 v[132:147], v[116:123], v[148:155], v[68:83]
.LBB0_650:
	v_sub_co_u32_e64 v0, s[38:39], s62, 1
	s_and_b64 s[38:39], s[38:39], exec
	v_readfirstlane_b32 s9, v0
	s_cselect_b32 s60, 5, s9
	s_mov_b32 s32, s60
	s_add_i32 s9, s62, 1
	s_cmp_lg_u32 s62, 5
	s_cselect_b32 s9, s9, 0
	s_lshl_b32 s61, s60, 13
	v_add_u32_e32 v2, s61, v239
	v_add_u32_e32 v250, s61, v240
	v_lshl_add_u32 v0, s62, 12, v238
	v_add_u32_e32 v1, v0, v231
	v_add_u32_e32 v0, v0, v232
	ds_read_b128 v[242:245], v1
	ds_read_b128 v[202:205], v1 offset:2048
	ds_read_b128 v[246:249], v0
	ds_read_b128 v[206:209], v0 offset:2048
	v_exp_f32_e32 v100, v100
	v_exp_f32_e32 v101, v101
	v_exp_f32_e32 v102, v102
	v_exp_f32_e32 v103, v103
	v_exp_f32_e32 v104, v104
	v_exp_f32_e32 v105, v105
	v_exp_f32_e32 v106, v106
	v_exp_f32_e32 v107, v107
	v_pk_add_f32 v[0:1], v[100:101], v[102:103]
	v_pk_add_f32 v[252:253], v[104:105], v[106:107]
	v_mfma_f32_32x32x64_f8f6f4 v[116:131], v[188:195], v[148:155], v[68:83]
	v_exp_f32_e32 v108, v108
	v_exp_f32_e32 v109, v109
	v_exp_f32_e32 v110, v110
	v_exp_f32_e32 v111, v111
	v_exp_f32_e32 v112, v112
	v_exp_f32_e32 v113, v113
	v_exp_f32_e32 v114, v114
	v_exp_f32_e32 v115, v115
	v_pk_add_f32 v[0:1], v[108:109], v[0:1]
	v_pk_add_f32 v[252:253], v[252:253], v[110:111]
	v_pk_add_f32 v[0:1], v[112:113], v[0:1]
	v_pk_add_f32 v[252:253], v[252:253], v[114:115]
	v_mfma_f32_32x32x64_f8f6f4 v[132:147], v[180:187], v[156:163], v[132:147]
	v_exp_f32_e32 v84, v84
	v_exp_f32_e32 v85, v85
	v_exp_f32_e32 v86, v86
	v_exp_f32_e32 v87, v87
	v_exp_f32_e32 v88, v88
	v_exp_f32_e32 v89, v89
	v_exp_f32_e32 v90, v90
	v_exp_f32_e32 v91, v91
	v_pk_add_f32 v[0:1], v[84:85], v[0:1]
	v_pk_add_f32 v[252:253], v[252:253], v[86:87]
	v_pk_add_f32 v[0:1], v[88:89], v[0:1]
	v_pk_add_f32 v[252:253], v[252:253], v[90:91]
	v_mfma_f32_32x32x64_f8f6f4 v[116:131], v[172:179], v[156:163], v[116:131]
	ds_read_b64 v[182:183], v250
	ds_read_b64 v[176:177], v250 offset:2048
	ds_read_b128 v[178:181], v2
	ds_read_b128 v[172:175], v2 offset:2048
	v_exp_f32_e32 v92, v92
	v_exp_f32_e32 v93, v93
	v_exp_f32_e32 v94, v94
	v_exp_f32_e32 v95, v95
	v_exp_f32_e32 v96, v96
	v_exp_f32_e32 v97, v97
	v_exp_f32_e32 v98, v98
	v_exp_f32_e32 v99, v99
	v_pk_add_f32 v[0:1], v[92:93], v[0:1]
	v_pk_add_f32 v[252:253], v[252:253], v[94:95]
	v_pk_add_f32 v[0:1], v[96:97], v[0:1]
	v_pk_add_f32 v[252:253], v[252:253], v[98:99]
	v_cvt_scalef32_2xpk16_bf6_f32 v[196:201], v[100:115], v[84:99], 1.0
	v_pk_add_f32 v[0:1], v[0:1], v[252:253]
	s_waitcnt lgkmcnt(4)
	v_mfma_f32_32x32x64_f8f6f4 v[132:147], v[242:249], v[164:171], v[132:147]
	s_nop 0
	v_pk_add_f32 v[0:1], v[0:1], v[0:1] op_sel:[0,1] op_sel_hi:[1,0]
	s_nop 0
	v_mov_b32_e32 v1, v0
	s_nop 1
	v_permlane32_swap_b32_e32 v0, v1
	v_mfma_f32_32x32x64_f8f6f4 v[116:131], v[202:209], v[164:171], v[116:131]
	s_waitcnt lgkmcnt(0)
	v_mfma_f32_32x32x64_f8f6f4 v[52:67], v[196:201], v[178:183], v[52:67] cbsz:3 blgp:2
	ds_read_b64 v[102:103], v250 offset:4096
	ds_read_b64 v[96:97], v250 offset:6144
	ds_read_b128 v[98:101], v2 offset:4096
	ds_read_b128 v[92:95], v2 offset:6144
	v_max3_f32 v84, v132, v133, v134
	v_max3_f32 v2, v135, v136, v137
	v_max3_f32 v84, v84, v138, v139
	s_nop 0
	v_max3_f32 v2, v2, v140, v141
	v_max3_f32 v84, v84, v142, v143
	s_nop 0
	v_max3_f32 v2, v2, v144, v145
	v_max3_f32 v84, v84, v146, v147
	v_mfma_f32_32x32x64_f8f6f4 v[36:51], v[196:201], v[172:177], v[36:51] cbsz:3 blgp:2
	v_lshl_add_u32 v105, s9, 13, v233
	v_max3_f32 v84, v84, v116, v117
	v_add_u32_e32 v88, v105, v234
	v_add_u32_e32 v106, v105, v235
	v_max3_f32 v104, v84, v120, v121
	ds_read_b128 v[84:87], v88 offset:49152
	ds_read_b128 v[188:191], v88 offset:53248
	ds_read_b128 v[88:91], v106 offset:49152
	ds_read_b128 v[192:195], v106 offset:53248
	v_add_u32_e32 v106, v105, v236
	v_add_u32_e32 v105, v105, v237
	ds_read_b128 v[180:183], v106 offset:49152
	ds_read_b128 v[172:175], v106 offset:53248
	ds_read_b128 v[184:187], v105 offset:49152
	ds_read_b128 v[176:179], v105 offset:53248
	v_max3_f32 v2, v2, v118, v119
	v_max3_f32 v104, v104, v124, v125
	s_nop 0
	v_max3_f32 v2, v2, v122, v123
	v_max3_f32 v104, v104, v128, v129
	s_nop 0
	v_max3_f32 v2, v2, v126, v127
	s_nop 0
	v_max3_f32 v2, v2, v130, v131
	s_waitcnt lgkmcnt(8)
	v_mfma_f32_32x32x64_f8f6f4 v[20:35], v[196:201], v[98:103], v[20:35] cbsz:3 blgp:2
	v_max_f32_e32 v2, v2, v2
	v_max_f32_e32 v98, v104, v104
	v_max_f32_e32 v2, v98, v2
	v_mov_b32_e32 v98, v2
	s_nop 1
	v_permlane32_swap_b32_e32 v2, v98
	v_max_f32_e32 v98, v98, v98
	v_max_f32_e32 v2, v2, v2
	v_max_f32_e32 v2, v2, v98
	v_cmp_ge_f32_e32 vcc, s0, v2
	s_cmp_eq_u64 vcc, exec
	s_cbranch_scc0 .LBB0_683
	v_mov_b32_e32 v242, 1.0

.LBB0_671:
	s_waitcnt vmcnt(0)
	s_waitcnt lgkmcnt(0)
	s_barrier
	v_mfma_f32_32x32x64_f8f6f4 v[132:147], v[116:123], v[148:155], v[68:83]
	s_add_i32 s58, s2, -1
	s_cmp_ge_u32 s58, s92
	s_cbranch_scc1 .Lattn_xdone
	s_lshl_b32 s58, s32, 13
	s_add_i32 s58, s8, s58
	v_lshl_add_u64 v[124:125], v[218:219], 0, s[96:97]
	s_mov_b32 m0, s58
	s_and_b64 vcc, exec, s[38:39]
	global_load_lds_dwordx4 v[124:125], off
	v_lshl_add_u64 v[124:125], v[216:217], 0, s[96:97]
	s_add_i32 m0, s58, 0xc000
	s_nop 0
	global_load_lds_dwordx4 v[124:125], off
	s_cbranch_vccnz .Lattn_xdone
	s_mov_b32 s100, 0xfffff000
	s_mov_b32 s101, -1
	s_lshl_b32 s59, s32, 12
	v_lshl_add_u64 v[124:125], v[210:211], 0, s[100:101]
	s_add_i32 m0, s57, s59
	s_nop 0
	global_load_lds_dwordx4 v[124:125], off
